# GLA static priority raise applied to odd waves (1,3,5,7) instead of waves 4-7
# speedup vs baseline: 1.0032x; 1.0006x over previous
; #define LAS __attribute__((address_space(3)))
; __device__ __forceinline__ int bid_() { int v = __builtin_amdgcn_readfirstlane((int)blockIdx.x); asm volatile("" : "+s"(v)); return v; }
; __device__ __forceinline__ int nblk_() { int v = __builtin_amdgcn_readfirstlane((int)gridDim.x); asm volatile("" : "+s"(v)); return v; }
; template <bool PASS2>
; __device__ __forceinline__ void gla_pass(LAS unsigned char* lds, const Params& p, int layer) {
;     constexpr int SQ = 0, SK = 17408, SV = 35840, SP = 69632, SLR = 78848, SDEC = 84992, SST = 85504, SX = SST, SCOL = SST + 33792;
;     int tid = threadIdx.x; asm volatile("" : "+v"(tid));
;     const int wid = __builtin_amdgcn_readfirstlane(tid >> 6), lane = tid & 63, fr = lane & 15, fq = lane >> 4;
;     const int dk0 = (tid & 63) * 2;
;     bf16_t* P = (bf16_t*)(p.ws + OFF_PROJ);
;     const bf16_t* LR = (const bf16_t*)(p.ws + OFF_LR);
;     bf16_t* QT = (bf16_t*)(p.ws + OFF_E + (size_t)32 * 1024 * 1024);
;     bf16_t* O = (bf16_t*)(p.ws + OFF_O);
;     for (int item = bid_(); item < 256; item += nblk_()) {
;         const int b = item >> 7, h = (item >> 5) & 3, grp = item & 31;
; #pragma unroll 1
;         for (int dir = 0; dir < 2; ++dir) {
;             const int scan = (b * 4 + h) * 2 + dir;
;             bf16x8 wB1, wB2; float biasx;
;             { const float* Wc = (dir ? p.wdu_b : p.wdu_f) + (size_t)layer * 16 * 512 + h * 128 + wid * 16 + fr;
.LBB0_439:
	s_andn2_b64 vcc, exec, s[0:1]
	s_mov_b32 s30, s70
	s_cbranch_vccnz .LBB0_608
	v_readlane_b32 s0, v254, 34
	s_cmp_gt_i32 s0, 0
	s_mov_b64 s[0:1], -1
	s_cbranch_scc0 .LBB0_518
	v_writelane_b32 v254, s72, 35
	s_waitcnt vmcnt(0) lgkmcnt(0)
	v_mov_b32_e32 v1, v144
	s_cmpk_gt_i32 s60, 0xff
	v_writelane_b32 v254, s73, 36
	v_readfirstlane_b32 s0, v1
	s_cbranch_scc1 .LBB0_517
	v_readlane_b32 s6, v254, 25
	s_movk_i32 s1, 0x100
	v_readlane_b32 s7, v254, 26
	s_add_u32 s18, s6, 0x16200000
	v_cmp_gt_i32_e64 s[12:13], s1, v1
	s_movk_i32 s1, 0xff
	s_addc_u32 s19, s7, 0
	s_ashr_i32 s82, s0, 6
	s_bitcmp0_b32 s82, 0
	s_cbranch_scc1 .Lgla_prio_done
	s_setprio 1
